# speedup vs baseline: 1.0502x; 1.0039x over previous
; #define LAS __attribute__((address_space(3)))
; #define LOAD_K(t) do { _Pragma("unroll") for (int i = 0; i < KCH; ++i) kreg[i] = *(const u32x4*)((const char*)kg + (size_t)((t) * 64 + i * RPPK) * (LD * 2) + kvoff); } while (0)
; #define LOAD_V(t) do { _Pragma("unroll") for (int i = 0; i < VCH; ++i) vreg[i] = *(const u32x4*)((const char*)vg + (size_t)((t) * 64 + i * RPPV) * (LD * 2) + vvoff); \
;         if (MODE == 2 && tid < 64) fkreg = X.F2[(size_t)(b * 16 + hd) * SEQ + (t) * 64 + tid]; } while (0)
; #define STORE_K(buf) do { _Pragma("unroll") for (int i = 0; i < KCH; ++i) *(LAS u32x4*)(lds + (buf) * STG + klds + i * RPPK * PK) = kreg[i]; } while (0)
; #define STORE_V(buf) do { _Pragma("unroll") for (int i = 0; i < VCH; ++i) *(LAS u32x4*)(lds + (buf) * STG + vlds + i * RPPV * PV) = vreg[i]; \
;         if (MODE == 2 && tid < 64) fkb[(buf) * 64 + tid] = fkreg; } while (0)
; template <int MODE>
; __device__ __forceinline__ void attn_unit(LAS unsigned char* lds, const bf16_t* __restrict__ qkvz, bf16_t* __restrict__ A2, const int b, const int hd, const int qb, const AttnX& X, const int tid) {
;     ...
;     { const bf16_t* qp = qkvz + (rowbase + q0w + r32) * LD + qcol + 8 * hh;
; #pragma unroll
;       for (int s = 0; s < NS; ++s) qf[s] = *(const bf16x8*)(qp + 16 * s); }
;     LAS float* fkb = (LAS float*)(lds + XOFF);
;     LAS float* tbl = (LAS float*)(lds + XOFF);
;     if (MODE == 1) { for (int i = tid; i < 513; i += NTHREADS) tbl[i] = X.rel[hd * 513 + i] * LOG2E; }
;     ...
;     const unsigned kvoff = ((utid / KCPR) * LD + (utid % KCPR) * 8) * 2, vvoff = ((utid / VCPR) * LD + (utid % VCPR) * 8) * 2;
;     const unsigned klds = (utid / KCPR) * PK + (utid % KCPR) * 16, vlds = KSZ + (utid / VCPR) * PV + (utid % VCPR) * 16;
;     ...
;     f32x16 O[NDT];
; #pragma unroll
;     for (int d = 0; d < NDT; ++d)
; #pragma unroll
;         for (int i = 0; i < 16; ++i) O[d][i] = 0.f;
;     float m_run = -1e30f, l_run = 0.f;
;     constexpr bool DESC = (MODE == 2);
;     const int NT = kt_hi - kt_lo + 1;
;     ...
;     LOAD_K(TILE(0)); LOAD_V(TILE(0)); STORE_K(0); STORE_V(0);
.LBB0_586:
	v_readfirstlane_b32 s0, v122
	s_and_b32 s40, s38, 31
	s_ashr_i32 s0, s0, 1
	s_ashr_i32 s28, s38, 10
	s_lshl_b32 s12, s40, 8
	s_andn2_b32 s0, s0, 31
	s_add_i32 s39, s0, s12
	s_ashr_i32 s29, s28, 31
	s_bfe_u32 s1, s38, 0x50005
	s_lshl_b64 s[12:13], s[28:29], 13
	s_ashr_i32 s14, s39, 31
	s_add_u32 s12, s12, s39
	s_addc_u32 s13, s13, s14
	v_mov_b32_e32 v1, s13
	v_or_b32_e32 v0, s12, v124
	v_lshlrev_b64 v[0:1], 14, v[0:1]
	v_lshl_add_u64 v[0:1], s[84:85], 0, v[0:1]
	s_lshl_b32 s14, s1, 7
	v_lshl_add_u64 v[0:1], v[0:1], 0, s[14:15]
	v_lshl_add_u64 v[0:1], v[0:1], 0, v[128:129]
	global_load_dwordx4 v[98:101], v[0:1], off
	global_load_dwordx4 v[102:105], v[0:1], off offset:32
	global_load_dwordx4 v[106:109], v[0:1], off offset:64
	global_load_dwordx4 v[110:113], v[0:1], off offset:96
	s_lshl_b32 s44, s40, 2
	v_sub_u32_e64 v2, s44, 8 clamp
	v_mov_b32_e32 v3, 0
	s_lshl_b64 s[46:47], s[28:29], 27
	s_add_u32 s46, s84, s46
	s_addc_u32 s47, s85, s47
	s_lshl_b32 s45, s1, 7
	s_add_u32 s46, s46, s45
	s_addc_u32 s47, s47, 0
	v_lshlrev_b32_e32 v2, 20, v2
	s_add_u32 s44, s46, 0x1000
	s_addc_u32 s45, s47, 0
	v_lshl_add_u64 v[0:1], s[44:45], 0, v[2:3]
	v_lshl_add_u64 v[0:1], v[0:1], 0, v[126:127]
	global_load_dwordx4 v[114:117], v[0:1], off
	s_add_u32 s44, s46, 0x2000
	s_addc_u32 s45, s47, 0
	v_lshl_add_u64 v[0:1], s[44:45], 0, v[2:3]
	v_lshl_add_u64 v[0:1], v[0:1], 0, v[126:127]
	global_load_dwordx4 v[118:121], v[0:1], off
	s_and_saveexec_b64 s[12:13], s[2:3]
	s_cbranch_execz .LBB0_601
	s_mov_b64 s[34:35], -1
	v_mov_b32_e32 v0, v122
	v_mov_b32_e32 v1, v136
	s_and_saveexec_b64 s[30:31], s[4:5]
	s_cbranch_execz .LBB0_598
	s_mul_i32 s14, s1, 0x201
	v_mov_b32_e32 v4, 0
	v_mov_b64_e32 v[0:1], v[122:123]
	s_and_saveexec_b64 s[34:35], s[6:7]
	s_cbranch_execz .LBB0_592
	s_add_i32 s41, s14, 0x400
	s_add_i32 s43, s14, 0x800
	s_add_i32 s45, s14, 0xc00
	s_mov_b32 s42, s41
	s_mov_b32 s44, s43
	s_mov_b32 s46, s45
	s_mov_b32 s47, 0
	s_mov_b64 s[36:37], 0
	v_mov_b32_e32 v2, v140
	v_mov_b32_e32 v3, v142
	v_mov_b64_e32 v[0:1], v[122:123]

; #define LOAD_K(t) do { _Pragma("unroll") for (int i = 0; i < KCH; ++i) kreg[i] = *(const u32x4*)((const char*)kg + (size_t)((t) * 64 + i * RPPK) * (LD * 2) + kvoff); } while (0)
; #define LOAD_V(t) do { _Pragma("unroll") for (int i = 0; i < VCH; ++i) vreg[i] = *(const u32x4*)((const char*)vg + (size_t)((t) * 64 + i * RPPV) * (LD * 2) + vvoff); \
;         if (MODE == 2 && tid < 64) fkreg = X.F2[(size_t)(b * 16 + hd) * SEQ + (t) * 64 + tid]; } while (0)
; #define STORE_K(buf) do { _Pragma("unroll") for (int i = 0; i < KCH; ++i) *(LAS u32x4*)(lds + (buf) * STG + klds + i * RPPK * PK) = kreg[i]; } while (0)
; #define STORE_V(buf) do { _Pragma("unroll") for (int i = 0; i < VCH; ++i) *(LAS u32x4*)(lds + (buf) * STG + vlds + i * RPPV * PV) = vreg[i]; \
;         if (MODE == 2 && tid < 64) fkb[(buf) * 64 + tid] = fkreg; } while (0)
; template <int MODE>
; __device__ __forceinline__ void attn_unit(LAS unsigned char* lds, const bf16_t* __restrict__ qkvz, bf16_t* __restrict__ A2, const int b, const int hd, const int qb, const AttnX& X, const int tid) {
;     ...
;     const unsigned kvoff = ((utid / KCPR) * LD + (utid % KCPR) * 8) * 2, vvoff = ((utid / VCPR) * LD + (utid % VCPR) * 8) * 2;
;     const unsigned klds = (utid / KCPR) * PK + (utid % KCPR) * 16, vlds = KSZ + (utid / VCPR) * PV + (utid % VCPR) * 16;
;     ...
;     f32x16 O[NDT];
; #pragma unroll
;     for (int d = 0; d < NDT; ++d)
; #pragma unroll
;         for (int i = 0; i < 16; ++i) O[d][i] = 0.f;
;     float m_run = -1e30f, l_run = 0.f;
;     constexpr bool DESC = (MODE == 2);
;     const int NT = kt_hi - kt_lo + 1;
;     ...
;     LOAD_K(TILE(0)); LOAD_V(TILE(0)); STORE_K(0); STORE_V(0);
;     if (PF2 && NT > 1) { LOAD_K(TILE(1)); if (PF2V) LOAD_V(TILE(1)); }
.LBB0_601:
	s_or_b64 exec, exec, s[12:13]
	s_lshl_b32 s31, s40, 2
	s_lshl_b32 s1, s1, 6
	s_max_u32 s42, s31, 8
	s_or_b32 s30, s31, 3
	s_lshl_b64 s[12:13], s[28:29], 27
	s_add_u32 s12, s84, s12
	s_addc_u32 s13, s85, s13
	s_lshl_b32 s14, s1, 1
	s_add_u32 s1, s12, s14
	s_addc_u32 s29, s13, 0
	v_sub_u32_e64 v2, s31, 8 clamp
	s_add_u32 s12, s1, 0x1000
	s_addc_u32 s13, s29, 0
	v_lshlrev_b32_e32 v80, 20, v2
	s_add_u32 s34, s1, 0x2000
	v_lshl_add_u64 v[0:1], s[12:13], 0, v[80:81]
	s_addc_u32 s35, s29, 0
	v_lshl_add_u64 v[0:1], v[0:1], 0, v[126:127]
	v_lshl_add_u64 v[0:1], s[34:35], 0, v[80:81]
	v_lshl_add_u64 v[0:1], v[0:1], 0, v[126:127]
	v_readfirstlane_b32 s1, v2
	s_sub_i32 s29, s30, s1
	s_cmp_gt_i32 s29, 0
	s_waitcnt vmcnt(1)
	ds_write_b128 v134, v[114:117]
	s_waitcnt vmcnt(0)
	ds_write_b128 v135, v[118:121] offset:9216
	s_cbranch_scc0 .LBB0_603
	s_lshl_b32 s1, s42, 6
	s_add_i32 s36, s1, 0xfffffe40
	s_mov_b32 s37, s15
	s_lshl_b64 s[36:37], s[36:37], 14
	s_add_u32 s40, s12, s36
	s_addc_u32 s41, s13, s37
	s_add_u32 s36, s34, s36
	v_lshl_add_u64 v[0:1], s[40:41], 0, v[126:127]
	s_addc_u32 s37, s35, s37
	v_lshl_add_u64 v[2:3], s[36:37], 0, v[126:127]
	global_load_dwordx4 v[114:117], v[0:1], off
	global_load_dwordx4 v[118:121], v[2:3], off

; #define LAS __attribute__((address_space(3)))
; #define PHASE_IDS() const int tid = launder_v((int)threadIdx.x); const int lane = tid & 63; const int wid = __builtin_amdgcn_readfirstlane(tid >> 6); \
;     const int G = launder_s((int)gridDim.x); const int bx = launder_s((int)blockIdx.x); const int gw = bx * 8 + wid; const int ngw = G * 8; (void)lane; (void)gw; (void)ngw; \
;     unsigned char* const ws = p.ws; (void)ws
; __device__ __forceinline__ void phase_fox_cumsum(const Params& p, LAS unsigned char* lds) {
;     PHASE_IDS();
;     for (int it = bx; it < 256; it += G) { const int bh = it & 63, quarter = it >> 6, b = bh >> 4, h = bh & 15;
;         const bf16_t* Kp = (const bf16_t*)(ws + WS_QKVZ) + 2048 + h * 128; float* KN = (float*)(ws + WS_KN);
; #pragma unroll
;         for (int j = 0; j < 4; ++j) { const int key = quarter * 2048 + j * 512 + tid; const bf16_t* kr = Kp + ((size_t)b * SEQ + key) * 8192; float ss = 0.f;
.LBB0_918:
	s_or_b64 exec, exec, s[2:3]
	v_mov_b32_e32 v19, v212
	s_waitcnt lgkmcnt(0)
	s_barrier
	s_mov_b32 s3, s74
	v_and_b32_e32 v18, 63, v19
	s_mov_b32 s2, s92
	v_readfirstlane_b32 s0, v19
	v_cmp_eq_u32_e32 vcc, 0, v18
	s_mov_b32 s19, s2
	s_cmp_lt_u32 s3, 0x80
	s_cbranch_scc1 .Lkn_orig
	s_sub_i32 s19, s2, 64
	s_sub_i32 s3, s3, 64
	s_cmp_lt_i32 s19, 0
	s_cbranch_scc1 .LBB0_929
.Lkn_orig:
	s_cmpk_gt_i32 s19, 0xff
	s_cbranch_scc1 .LBB0_929
	s_ashr_i32 s12, s0, 6
	s_add_u32 s13, s72, 0x19801000
	s_addc_u32 s14, s73, 0
	s_add_u32 s15, s72, 0x93b0000
	s_addc_u32 s16, s73, 0
	s_mov_b32 s5, 0
	s_lshl_b32 s17, s19, 7
	s_lshl_b32 s18, s3, 7
	v_mov_b32_e32 v12, 0
	s_branch .LBB0_921
